# v25: as v24 with the slot preset stored write-through (sc0 sc1)
# baseline (speedup 1.0000x reference)
; __device__ __forceinline__ void xcd_barrier(const XcdBarrier& b) {
;     asm volatile("s_waitcnt vmcnt(0)" ::: "memory");
;     __syncthreads();
;     if (threadIdx.x == 0) {
;         unsigned* bar = b.bar;
;         __builtin_amdgcn_s_waitcnt(0);
;         unsigned nloc = b.st[0], nx = b.st[1];
;         if (nloc == 0u) { xcd_barrier_complete(bar, b.x, nloc, nx); b.st[0] = nloc; b.st[1] = nx; }
.LBB0_104:
	s_or_b64 exec, exec, s[14:15]
	s_load_dwordx2 s[4:5], s[0:1], 0xc8
	v_lshl_add_u32 v2, s81, 9, v0
	v_mov_b32_e32 v6, 0xbf800000
	v_cmp_gt_u32_e32 vcc, 0x10000, v2
	v_mov_b32_e32 v7, v6
	v_mov_b32_e32 v8, v6
	v_mov_b32_e32 v9, v6
	v_lshlrev_b32_e32 v2, 4, v2
	s_and_saveexec_b64 s[6:7], vcc
	s_waitcnt lgkmcnt(0)
	s_add_u32 s4, s4, 0x1f00000
	s_addc_u32 s5, s5, 0
	global_store_dwordx4 v2, v[6:9], s[4:5] sc0 sc1
	s_or_b64 exec, exec, s[6:7]
	s_waitcnt vmcnt(0)
	s_barrier
	s_and_saveexec_b64 s[4:5], s[22:23]
	s_cbranch_execz .LBB0_156
	s_add_i32 s3, 0, 0x20160
	v_mov_b32_e32 v1, s3
	s_waitcnt vmcnt(0) expcnt(0) lgkmcnt(0)
	ds_read_b32 v3, v1
	s_add_i32 s3, 0, 0x20164
	v_mov_b32_e32 v1, s3
	ds_read_b32 v1, v1
	s_waitcnt lgkmcnt(1)
	v_cmp_ne_u32_e32 vcc, 0, v3
	s_cbranch_vccnz .LBB0_120
	v_readlane_b32 s6, v237, 0
	v_readlane_b32 s7, v237, 1
	s_load_dwordx2 s[10:11], s[6:7], 0x4
	s_add_u32 s6, s64, 0x4200
	s_addc_u32 s7, s65, 0
	s_add_u32 s8, s64, 0x4400
	s_addc_u32 s9, s65, 0
	s_waitcnt lgkmcnt(0)
	s_mul_i32 s3, s10, s33
	s_add_u32 s10, s64, 0x4500
	s_mul_i32 s3, s3, s11
	s_addc_u32 s11, s65, 0
	s_add_u32 s14, s64, 0x4600
	s_addc_u32 s15, s65, 0
	s_add_u32 s16, s64, 0x4700
	s_addc_u32 s17, s65, 0
	s_add_u32 s18, s64, 0x4800
	s_addc_u32 s19, s65, 0
	s_add_u32 s20, s64, 0x4900
	s_addc_u32 s21, s65, 0
	s_add_u32 s36, s64, 0x4a00
	s_addc_u32 s37, s65, 0
	s_add_u32 s38, s64, 0x4b00
	s_addc_u32 s39, s65, 0
	s_add_u32 s40, s64, 0x4c00
	s_addc_u32 s41, s65, 0
	s_add_u32 s42, s64, 0x4d00
	s_addc_u32 s43, s65, 0
	s_add_u32 s44, s64, 0x4e00
	s_addc_u32 s45, s65, 0
	s_add_u32 s46, s64, 0x4f00
	s_addc_u32 s47, s65, 0
	s_add_u32 s48, s64, 0x5000
	s_addc_u32 s49, s65, 0
	s_add_u32 s50, s64, 0x5100
	s_addc_u32 s51, s65, 0
	s_add_u32 s52, s64, 0x5200
	s_addc_u32 s53, s65, 0
	s_add_u32 s54, s64, 0x5300
	s_addc_u32 s55, s65, 0
	s_mov_b32 s13, 1
	v_mov_b32_e32 v17, 0
	s_branch .LBB0_108
